# P6b K/V f32 and in-place bf16 stores routed through per-wave LDS scratch so each instruction writes 128 B to 1 KiB contiguous
# speedup vs baseline: 1.0207x; 1.0207x over previous
; DI float bflo(unsigned u) { return __uint_as_float(u << 16); }
; DI float bfhi(unsigned u) { return __uint_as_float(u & 0xffff0000u); }
; DI void qkv_post_chunk(const Params& p, unsigned char* lds, int c2) {
;     ...
;     const int hd = lane >> 3, d0 = (lane & 7) * 16;
;     float qn[16], kn[16];
; #pragma unroll
;     for (int e = 0; e < 16; ++e) { qn[e] = p.qn[d0 + e]; kn[e] = p.kn[d0 + e]; }
;     for (int bt = 0; bt < 1; ++bt) {
;         u32x4 ld[4][3][2];
; #pragma unroll
;         for (int j = 0; j < 4; ++j) { const bf16_t* rowp = QKV + (size_t)(tok0 + wave + 8 * (4 * bt + j)) * 3072 + lane * 16;
; #pragma unroll
;             for (int sec = 0; sec < 3; ++sec) { ld[j][sec][0] = *(const u32x4*)(rowp + sec * 1024); ld[j][sec][1] = *(const u32x4*)(rowp + sec * 1024 + 8); } }
; #pragma unroll
;         for (int j = 0; j < 4; ++j) {
;             const int tk = wave + 8 * (4 * bt + j);
;             bf16_t* rowp = QKV + (size_t)(tok0 + tk) * 3072;
; #pragma unroll
;             for (int sec = 0; sec < 3; ++sec) {
;                 bf16_t* pp = rowp + sec * 1024 + lane * 16;
;                 const u32x4 v0 = ld[j][sec][0], v1 = ld[j][sec][1];
;                 float x[16];
; #pragma unroll
;                 for (int e = 0; e < 4; ++e) { x[2 * e] = bflo(v0[e]); x[2 * e + 1] = bfhi(v0[e]); x[8 + 2 * e] = bflo(v1[e]); x[8 + 2 * e + 1] = bfhi(v1[e]); }
.LBB0_125:
	v_and_b32_e32 v240, 63, v202
	v_lshrrev_b32_e32 v241, 6, v202
	v_and_b32_e32 v242, 7, v202
	v_lshlrev_b32_e32 v241, 12, v241
	v_add_u32_e32 v241, 0x12000, v241
	v_mul_u32_u24_e32 v242, 48, v242
	v_lshrrev_b32_e32 v243, 3, v240
	v_mul_u32_u24_e32 v243, 0x180, v243
	v_lshl_add_u32 v243, v240, 4, v243
	v_lshl_add_u32 v240, v240, 6, v241
	v_add_u32_e32 v241, v241, v243
	v_sub_u32_e32 v242, 0, v242
	v_ashrrev_i32_e32 v243, 31, v242
	v_and_b32_e32 v246, 63, v202
	v_lshrrev_b32_e32 v247, 6, v202
	v_lshlrev_b32_e32 v247, 12, v247
	v_add_u32_e32 v247, 0x12000, v247
	v_lshlrev_b32_e32 v248, 4, v246
	v_lshl_add_u32 v246, v246, 5, v247
	v_add_u32_e32 v247, v247, v248
	v_sub_u32_e32 v248, 0, v248
	v_ashrrev_i32_e32 v249, 31, v248
	s_addk_i32 s29, 0xff00
	s_ashr_i32 s1, s16, 8
	s_and_b64 s[30:31], exec, s[4:5]
	s_cselect_b32 s1, s29, s1
	s_lshl_b32 s21, s29, 6
	s_addk_i32 s21, 0x4000
	s_and_b64 s[30:31], exec, s[4:5]
	s_cselect_b32 s21, s21, s28
	s_lshl_b32 s16, s16, 5
	v_and_b32_e32 v0, 63, v128
	s_and_b32 s16, s16, 32
	v_readlane_b32 s28, v253, 5
	v_ashrrev_i32_e32 v112, 6, v128
	s_or_b32 s25, s21, s16
	v_lshlrev_b32_e32 v124, 5, v0
	v_mov_b32_e32 v125, v181
	v_readlane_b32 s29, v253, 6
	v_add_u32_e32 v8, s25, v112
	v_lshlrev_b32_e32 v9, 6, v128
	v_lshl_add_u64 v[114:115], s[28:29], 0, v[124:125]
	v_mad_i64_i32 v[122:123], s[28:29], v8, s91, v[114:115]
	global_load_dwordx4 v[0:3], v[122:123], off offset:16
	global_load_dwordx4 v[4:7], v[122:123], off
	global_load_dwordx4 v[28:31], v[122:123], off offset:2048
	global_load_dwordx4 v[32:35], v[122:123], off offset:2064
	v_bfe_u32 v10, v128, 3, 3
	v_cmp_lt_i32_e32 vcc, v193, v195
	v_readlane_b32 s28, v252, 0
	s_lshl_b32 s1, s1, 3
	s_movk_i32 s15, 0x1000
	v_cndmask_b32_e32 v11, v192, v193, vcc
	v_and_b32_e32 v180, 0x1c0, v9
	v_readlane_b32 s29, v252, 1
	v_readlane_b32 s30, v252, 2
	v_readlane_b32 s31, v252, 3
	v_or_b32_e32 v113, s1, v10
	v_add_u32_e32 v12, 8, v8
	v_add_co_u32_e32 v10, vcc, s15, v122
	v_lshlrev_b32_e32 v125, 2, v11
	v_lshl_add_u64 v[116:117], s[30:31], 0, v[180:181]
	s_mov_b64 s[30:31], 0x1000
	v_addc_co_u32_e32 v11, vcc, 0, v123, vcc
	v_mad_i64_i32 v[12:13], s[28:29], v12, s91, v[114:115]
	v_add_u32_e32 v14, 16, v8
	v_add_u32_e32 v16, 24, v8
	v_lshl_add_u64 v[8:9], v[122:123], 0, s[30:31]
	global_load_dwordx4 v[88:91], v[10:11], off
	global_load_dwordx4 v[92:95], v[8:9], off offset:16
	global_load_dwordx4 v[104:107], v[12:13], off
	global_load_dwordx4 v[108:111], v[12:13], off offset:16
	global_load_dwordx4 v[96:99], v[12:13], off offset:2048
	global_load_dwordx4 v[100:103], v[12:13], off offset:2064
	v_add_co_u32_e32 v10, vcc, s15, v12
	v_mad_i64_i32 v[14:15], s[28:29], v14, s91, v[114:115]
	s_nop 0
	v_addc_co_u32_e32 v11, vcc, 0, v13, vcc
	v_lshl_add_u64 v[8:9], v[12:13], 0, s[30:31]
	global_load_dwordx4 v[80:83], v[14:15], off
	global_load_dwordx4 v[84:87], v[14:15], off offset:16
	global_load_dwordx4 v[72:75], v[14:15], off offset:2048
	global_load_dwordx4 v[76:79], v[14:15], off offset:2064
	v_lshl_add_u64 v[12:13], v[14:15], 0, s[30:31]
	v_add_co_u32_e32 v14, vcc, s15, v14
	v_readlane_b32 s44, v254, 29
	v_mad_i64_i32 v[120:121], s[28:29], v16, s91, v[114:115]
	v_addc_co_u32_e32 v15, vcc, 0, v15, vcc
	v_readlane_b32 s52, v254, 37
	v_readlane_b32 s53, v254, 38
	global_load_dwordx4 v[56:59], v[120:121], off
	global_load_dwordx4 v[60:63], v[120:121], off offset:16
	global_load_dwordx4 v[48:51], v[120:121], off offset:2048
	global_load_dwordx4 v[52:55], v[120:121], off offset:2064
	global_load_dwordx4 v[64:67], v[10:11], off
	global_load_dwordx4 v[68:71], v[8:9], off offset:16
	s_nop 0
	global_load_dwordx4 v[8:11], v[14:15], off
	s_nop 0
	global_load_dwordx4 v[12:15], v[12:13], off offset:16
	v_readlane_b32 s54, v254, 39
	v_readlane_b32 s55, v254, 40
	v_lshl_add_u64 v[126:127], v[120:121], 0, s[30:31]
	s_or_b32 s17, s17, s16
	v_mov_b32_e32 v119, v181
	v_mov_b32_e32 v118, s17
	v_mad_i64_i32 v[118:119], s[26:27], s26, v113, v[118:119]
	s_mov_b32 s26, 0x358637bd
	s_brev_b32 s28, 60
	v_ashrrev_i32_e32 v113, 31, v112
	s_lshl_b32 s92, s24, 2
	s_lshl_b32 s20, s20, 2
	s_mov_b32 s21, s93
	v_readlane_b32 s45, v254, 30
	v_readlane_b32 s46, v254, 31
	v_readlane_b32 s47, v254, 32
	v_readlane_b32 s48, v254, 33
	v_readlane_b32 s49, v254, 34
	v_readlane_b32 s50, v254, 35
	v_readlane_b32 s51, v254, 36
	v_readlane_b32 s56, v254, 41
	v_readlane_b32 s57, v254, 42
	v_readlane_b32 s58, v254, 43
	v_readlane_b32 s59, v254, 44
	s_waitcnt vmcnt(21)
	v_lshlrev_b32_e32 v132, 16, v3
	v_and_b32_e32 v133, 0xffff0000, v3
	v_lshlrev_b32_e32 v134, 16, v2
	v_and_b32_e32 v135, 0xffff0000, v2
	v_lshlrev_b32_e32 v136, 16, v1
	v_and_b32_e32 v137, 0xffff0000, v1
	v_lshlrev_b32_e32 v138, 16, v0
	v_and_b32_e32 v139, 0xffff0000, v0
	s_waitcnt vmcnt(20)
	v_lshlrev_b32_e32 v140, 16, v7
	v_and_b32_e32 v141, 0xffff0000, v7
	v_lshlrev_b32_e32 v148, 16, v6
	v_and_b32_e32 v149, 0xffff0000, v6
	v_lshlrev_b32_e32 v150, 16, v5
	v_and_b32_e32 v151, 0xffff0000, v5
	v_lshlrev_b32_e32 v152, 16, v4
	v_and_b32_e32 v153, 0xffff0000, v4
	global_load_dwordx4 v[24:27], v180, s[52:53] offset:48
	global_load_dwordx4 v[0:3], v180, s[54:55] offset:48
	global_load_dwordx4 v[36:39], v180, s[52:53] offset:32
	global_load_dwordx4 v[4:7], v180, s[54:55] offset:32
	global_load_dwordx4 v[40:43], v180, s[52:53] offset:16
	global_load_dwordx4 v[16:19], v180, s[54:55] offset:16
	global_load_dwordx4 v[44:47], v180, s[52:53]
	global_load_dwordx4 v[20:23], v180, s[54:55]
	s_waitcnt vmcnt(27)
; DI float bflo(unsigned u) { return __uint_as_float(u << 16); }
; DI float bfhi(unsigned u) { return __uint_as_float(u & 0xffff0000u); }
; DI void qkv_post_chunk(const Params& p, unsigned char* lds, int c2) {
;     ...
;             for (int sec = 0; sec < 3; ++sec) {
;                 bf16_t* pp = rowp + sec * 1024 + lane * 16;
;                 const u32x4 v0 = ld[j][sec][0], v1 = ld[j][sec][1];
;                 float x[16];
; #pragma unroll
;                 for (int e = 0; e < 4; ++e) { x[2 * e] = bflo(v0[e]); x[2 * e + 1] = bfhi(v0[e]); x[8 + 2 * e] = bflo(v1[e]); x[8 + 2 * e + 1] = bfhi(v1[e]); }
;                 if (sec < 2) {
;                     float ss = 0.f;
; #pragma unroll
;                     for (int e = 0; e < 16; ++e) ss += x[e] * x[e];
;                     ss += __shfl_xor(ss, 1); ss += __shfl_xor(ss, 2); ss += __shfl_xor(ss, 4);
;                     const float rs = rsqrtf(ss * (1.f / 128.f) + EPS);
; #pragma unroll
;                     for (int e = 0; e < 16; ++e) x[e] = x[e] * rs * (sec == 0 ? qn[e] : kn[e]);
	v_and_b32_e32 v173, 0xffff0000, v28
	v_lshlrev_b32_e32 v172, 16, v28
	v_mov_b32_e32 v212, v173
	v_mov_b32_e32 v213, v153
	v_lshlrev_b32_e32 v170, 16, v29
	v_mov_b32_e32 v188, v172
	v_mov_b32_e32 v189, v152
	v_pk_mul_f32 v[212:213], v[212:213], v[212:213]
	v_and_b32_e32 v171, 0xffff0000, v29
	v_mov_b32_e32 v178, v170
	v_mov_b32_e32 v179, v150
	v_pk_fma_f32 v[188:189], v[188:189], v[188:189], v[212:213]
	v_lshlrev_b32_e32 v168, 16, v30
	v_mov_b32_e32 v182, v171
	v_mov_b32_e32 v183, v151
	v_pk_fma_f32 v[178:179], v[178:179], v[178:179], v[188:189]
	v_and_b32_e32 v169, 0xffff0000, v30
	v_mov_b32_e32 v174, v168
	v_mov_b32_e32 v175, v148
	v_pk_fma_f32 v[178:179], v[182:183], v[182:183], v[178:179]
	v_lshlrev_b32_e32 v166, 16, v31
	v_mov_b32_e32 v176, v169
	v_mov_b32_e32 v177, v149
	v_pk_fma_f32 v[174:175], v[174:175], v[174:175], v[178:179]
	s_waitcnt vmcnt(26)
	v_lshlrev_b32_e32 v164, 16, v32
	v_and_b32_e32 v165, 0xffff0000, v32
	v_and_b32_e32 v167, 0xffff0000, v31
	v_mov_b32_e32 v28, v166
	v_mov_b32_e32 v29, v140
	v_pk_fma_f32 v[174:175], v[176:177], v[176:177], v[174:175]
	v_pk_mul_f32 v[146:147], v[138:139], v[138:139]
	v_lshlrev_b32_e32 v160, 16, v33
	v_and_b32_e32 v161, 0xffff0000, v33
	v_pk_mul_f32 v[32:33], v[164:165], v[164:165]
	v_mov_b32_e32 v30, v167
	v_mov_b32_e32 v31, v141
	v_pk_fma_f32 v[28:29], v[28:29], v[28:29], v[174:175]
	v_pk_mul_f32 v[144:145], v[136:137], v[136:137]
	v_pk_fma_f32 v[28:29], v[30:31], v[30:31], v[28:29]
	v_mov_b32_e32 v30, v32
	v_mov_b32_e32 v31, v146
	v_pk_mul_f32 v[162:163], v[160:161], v[160:161]
	v_pk_add_f32 v[28:29], v[30:31], v[28:29]
	v_mov_b32_e32 v146, v33
	v_lshlrev_b32_e32 v158, 16, v34
	v_and_b32_e32 v159, 0xffff0000, v34
	v_pk_add_f32 v[28:29], v[146:147], v[28:29]
	v_mov_b32_e32 v30, v162
	v_mov_b32_e32 v31, v144
	v_pk_mul_f32 v[142:143], v[134:135], v[134:135]
	v_lshlrev_b32_e32 v154, 16, v35
	v_and_b32_e32 v155, 0xffff0000, v35
	v_pk_mul_f32 v[34:35], v[158:159], v[158:159]
	v_pk_add_f32 v[28:29], v[30:31], v[28:29]
	v_mov_b32_e32 v144, v163
	v_pk_add_f32 v[28:29], v[144:145], v[28:29]
	v_mov_b32_e32 v30, v34
	v_mov_b32_e32 v31, v142
	v_pk_mul_f32 v[130:131], v[132:133], v[132:133]
	v_pk_mul_f32 v[156:157], v[154:155], v[154:155]
	v_pk_add_f32 v[28:29], v[30:31], v[28:29]
	v_mov_b32_e32 v142, v35
	v_pk_add_f32 v[28:29], v[142:143], v[28:29]
	v_mov_b32_e32 v30, v156
	v_mov_b32_e32 v31, v130
	v_pk_add_f32 v[28:29], v[30:31], v[28:29]
	v_mov_b32_e32 v130, v157
	v_pk_add_f32 v[28:29], v[130:131], v[28:29]
	ds_bpermute_b32 v31, v125, v29
	ds_bpermute_b32 v30, v125, v28
	v_add_co_u32_e32 v32, vcc, s15, v120
	s_waitcnt vmcnt(23)
	v_and_b32_e32 v163, 0xffff0000, v104
	v_addc_co_u32_e32 v33, vcc, 0, v121, vcc
	v_cmp_lt_i32_e32 vcc, v196, v195
	s_waitcnt lgkmcnt(0)
	v_pk_add_f32 v[120:121], v[28:29], v[30:31]
	s_waitcnt vmcnt(21)
	v_and_b32_e32 v179, 0xffff0000, v96
	v_cndmask_b32_e32 v34, v192, v196, vcc
	v_lshlrev_b32_e32 v129, 2, v34
	ds_bpermute_b32 v143, v129, v121
	ds_bpermute_b32 v142, v129, v120
	v_cmp_lt_i32_e32 vcc, v197, v195
	global_load_dwordx4 v[32:35], v[32:33], off
	s_nop 0
	global_load_dwordx4 v[28:31], v[126:127], off offset:16
	v_cndmask_b32_e32 v126, v192, v197, vcc
	v_lshlrev_b32_e32 v130, 2, v126
	s_waitcnt lgkmcnt(0)
	v_pk_add_f32 v[120:121], v[120:121], v[142:143]
	ds_bpermute_b32 v127, v130, v121
	ds_bpermute_b32 v126, v130, v120
	v_lshl_add_u64 v[142:143], v[118:119], 0, v[112:113]
	v_lshlrev_b64 v[142:143], 9, v[142:143]
	v_lshlrev_b32_e32 v162, 16, v104
	v_lshlrev_b32_e32 v178, 16, v96
	s_waitcnt lgkmcnt(0)
	v_pk_add_f32 v[126:127], v[120:121], v[126:127]
	v_mov_b64_e32 v[120:121], s[26:27]
	v_pk_fma_f32 v[144:145], v[126:127], s[28:29], v[120:121] op_sel_hi:[1,0,0]
	v_lshl_add_u64 v[126:127], v[116:117], 0, v[142:143]
	v_mul_f32_e32 v113, 0x4b800000, v145
	v_cmp_gt_f32_e32 vcc, s22, v145
	v_mov_b32_e32 v220, v179
	v_mov_b32_e32 v221, v163
	v_cndmask_b32_e32 v113, v145, v113, vcc
	v_rsq_f32_e32 v131, v113
	v_mul_lo_u32 v113, v112, s77
	v_add3_u32 v113, 0, v124, v113
	v_lshlrev_b32_e32 v176, 16, v98
	v_mul_f32_e32 v124, 0x45800000, v131
	v_cndmask_b32_e32 v124, v131, v124, vcc
	v_pk_mul_f32 v[142:143], v[124:125], v[152:153] op_sel_hi:[0,1]
	v_pk_mul_f32 v[146:147], v[124:125], v[150:151] op_sel_hi:[0,1]
	v_pk_mul_f32 v[148:149], v[124:125], v[148:149] op_sel_hi:[0,1]
	v_pk_mul_f32 v[140:141], v[124:125], v[140:141] op_sel_hi:[0,1]
	v_pk_mul_f32 v[138:139], v[124:125], v[138:139] op_sel_hi:[0,1]
	v_pk_mul_f32 v[136:137], v[124:125], v[136:137] op_sel_hi:[0,1]
	v_pk_mul_f32 v[134:135], v[124:125], v[134:135] op_sel_hi:[0,1]
	v_pk_mul_f32 v[132:133], v[124:125], v[132:133] op_sel_hi:[0,1]
	v_mul_f32_e32 v124, 0x4b800000, v144
	v_cmp_gt_f32_e32 vcc, s22, v144
	s_waitcnt vmcnt(3)
; DI unsigned cvt_pk_bf16(float lo, float hi) { const f32x2 v = {lo, hi}; const bf16x2_t b = __builtin_convertvector(v, bf16x2_t); return __builtin_bit_cast(unsigned, b); }
; DI void qkv_post_chunk(const Params& p, unsigned char* lds, int c2) {
;     ...
;                 if (sec < 2) {
;                     float ss = 0.f;
; #pragma unroll
;                     for (int e = 0; e < 16; ++e) ss += x[e] * x[e];
;                     ss += __shfl_xor(ss, 1); ss += __shfl_xor(ss, 2); ss += __shfl_xor(ss, 4);
;                     const float rs = rsqrtf(ss * (1.f / 128.f) + EPS);
; #pragma unroll
;                     for (int e = 0; e < 16; ++e) x[e] = x[e] * rs * (sec == 0 ? qn[e] : kn[e]);
;                     u32x4 w0, w1;
;                     w0.x = cvt_pk_bf16(x[0], x[1]); w0.y = cvt_pk_bf16(x[2], x[3]); w0.z = cvt_pk_bf16(x[4], x[5]); w0.w = cvt_pk_bf16(x[6], x[7]);
;                     w1.x = cvt_pk_bf16(x[8], x[9]); w1.y = cvt_pk_bf16(x[10], x[11]); w1.z = cvt_pk_bf16(x[12], x[13]); w1.w = cvt_pk_bf16(x[14], x[15]);
;                     *(u32x4*)pp = w0; *(u32x4*)(pp + 8) = w1;
;                 }
;                 if (sec >= 1) {
;                     float* o = (sec == 1 ? ko : vo) + ((size_t)(b * 8 + hd) * SL + s0 + tk) * 128 + d0;
; #pragma unroll
;                     for (int e4 = 0; e4 < 4; ++e4) *(f32x4*)(o + 4 * e4) = (f32x4){x[4 * e4], x[4 * e4 + 1], x[4 * e4 + 2], x[4 * e4 + 3]};
	v_pk_mul_f32 v[142:143], v[44:45], v[142:143]
	v_pk_mul_f32 v[156:157], v[26:27], v[132:133]
	v_cndmask_b32_e32 v124, v144, v124, vcc
	v_rsq_f32_e32 v124, v124
	v_cvt_pk_bf16_f32 v132, v142, v143
	v_and_b32_e32 v177, 0xffff0000, v98
	v_lshlrev_b32_e32 v98, 16, v97
	v_mul_f32_e32 v131, 0x45800000, v124
	v_cndmask_b32_e32 v124, v124, v131, vcc
	v_pk_mul_f32 v[142:143], v[124:125], v[160:161] op_sel_hi:[0,1]
	v_lshlrev_b32_e32 v160, 16, v106
	v_and_b32_e32 v161, 0xffff0000, v106
	v_lshlrev_b32_e32 v106, 16, v105
	v_mov_b32_e32 v218, v178
	v_mov_b32_e32 v219, v162
	v_pk_mul_f32 v[220:221], v[220:221], v[220:221]
	v_pk_mul_f32 v[146:147], v[46:47], v[146:147]
	v_pk_mul_f32 v[148:149], v[40:41], v[148:149]
	v_pk_mul_f32 v[140:141], v[42:43], v[140:141]
	v_pk_mul_f32 v[138:139], v[36:37], v[138:139]
	v_pk_mul_f32 v[150:151], v[38:39], v[136:137]
	v_pk_mul_f32 v[152:153], v[24:25], v[134:135]
	v_pk_mul_f32 v[144:145], v[124:125], v[158:159] op_sel_hi:[0,1]
	v_lshlrev_b32_e32 v158, 16, v107
	v_and_b32_e32 v159, 0xffff0000, v107
	v_and_b32_e32 v107, 0xffff0000, v105
	v_lshlrev_b32_e32 v174, 16, v99
	v_and_b32_e32 v175, 0xffff0000, v99
	v_and_b32_e32 v99, 0xffff0000, v97
	v_mov_b32_e32 v214, v98
	v_mov_b32_e32 v215, v106
	v_pk_fma_f32 v[218:219], v[218:219], v[218:219], v[220:221]
	v_cvt_pk_bf16_f32 v133, v146, v147
	v_cvt_pk_bf16_f32 v134, v148, v149
	v_cvt_pk_bf16_f32 v135, v140, v141
	v_cvt_pk_bf16_f32 v136, v138, v139
	v_cvt_pk_bf16_f32 v137, v150, v151
	v_cvt_pk_bf16_f32 v138, v152, v153
	v_cvt_pk_bf16_f32 v139, v156, v157
	v_mov_b32_e32 v216, v99
	v_mov_b32_e32 v217, v107
	v_pk_fma_f32 v[214:215], v[214:215], v[214:215], v[218:219]
	ds_write_b128 v246, v[132:135]
	ds_write_b128 v246, v[136:139] offset:16
	v_lshl_add_u64 v[250:251], v[122:123], 0, v[248:249]
	ds_read_b128 v[132:135], v247
	ds_read_b128 v[136:139], v247 offset:1024
	s_waitcnt lgkmcnt(0)
	global_store_dwordx4 v[250:251], v[132:135], off
	global_store_dwordx4 v[250:251], v[136:139], off offset:1024
	v_pk_mul_f32 v[140:141], v[124:125], v[164:165] op_sel_hi:[0,1]
	v_pk_mul_f32 v[132:133], v[124:125], v[172:173] op_sel_hi:[0,1]
	v_pk_mul_f32 v[134:135], v[124:125], v[170:171] op_sel_hi:[0,1]
	v_pk_mul_f32 v[136:137], v[124:125], v[168:169] op_sel_hi:[0,1]
	v_pk_mul_f32 v[138:139], v[124:125], v[166:167] op_sel_hi:[0,1]
	v_mov_b32_e32 v188, v176
	v_mov_b32_e32 v189, v160
	v_pk_fma_f32 v[214:215], v[216:217], v[216:217], v[214:215]
	s_waitcnt vmcnt(4)
	v_pk_mul_f32 v[132:133], v[20:21], v[132:133]
	v_pk_mul_f32 v[134:135], v[22:23], v[134:135]
	v_pk_mul_f32 v[136:137], v[16:17], v[136:137]
	v_pk_mul_f32 v[138:139], v[18:19], v[138:139]
	v_pk_mul_f32 v[140:141], v[4:5], v[140:141]
	v_pk_mul_f32 v[142:143], v[6:7], v[142:143]
	v_pk_mul_f32 v[146:147], v[124:125], v[154:155] op_sel_hi:[0,1]
	v_mov_b32_e32 v212, v177
	v_mov_b32_e32 v213, v161
	v_pk_fma_f32 v[188:189], v[188:189], v[188:189], v[214:215]
	v_pk_mul_f32 v[144:145], v[0:1], v[144:145]
	v_pk_mul_f32 v[146:147], v[2:3], v[146:147]
	v_cvt_pk_bf16_f32 v148, v132, v133
	v_cvt_pk_bf16_f32 v149, v134, v135
	v_cvt_pk_bf16_f32 v150, v136, v137
	v_cvt_pk_bf16_f32 v151, v138, v139
	v_cvt_pk_bf16_f32 v152, v140, v141
	v_cvt_pk_bf16_f32 v153, v142, v143
	v_lshlrev_b32_e32 v156, 16, v108
	v_and_b32_e32 v157, 0xffff0000, v108
	v_lshlrev_b32_e32 v172, 16, v100
	v_and_b32_e32 v173, 0xffff0000, v100
	v_mov_b32_e32 v96, v174
	v_mov_b32_e32 v97, v158
	v_pk_fma_f32 v[188:189], v[212:213], v[212:213], v[188:189]
	v_cvt_pk_bf16_f32 v154, v144, v145
	v_cvt_pk_bf16_f32 v155, v146, v147
	ds_write_b128 v246, v[148:151]
	ds_write_b128 v246, v[152:155] offset:16
	v_lshl_add_u64 v[250:251], v[122:123], 0, v[248:249]
	ds_read_b128 v[148:151], v247
	ds_read_b128 v[152:155], v247 offset:1024
	s_waitcnt lgkmcnt(0)
	global_store_dwordx4 v[250:251], v[148:151], off offset:2048
	global_store_dwordx4 v[250:251], v[152:155], off offset:3072
	v_lshlrev_b32_e32 v168, 16, v101
	v_and_b32_e32 v169, 0xffff0000, v101
	v_lshlrev_b32_e32 v152, 16, v109
	v_and_b32_e32 v153, 0xffff0000, v109
	v_pk_mul_f32 v[108:109], v[156:157], v[156:157]
	v_pk_mul_f32 v[100:101], v[172:173], v[172:173]
	v_mov_b32_e32 v182, v175
	v_mov_b32_e32 v183, v159
	v_pk_fma_f32 v[96:97], v[96:97], v[96:97], v[188:189]
	v_pk_mul_f32 v[154:155], v[152:153], v[152:153]
	v_pk_fma_f32 v[96:97], v[182:183], v[182:183], v[96:97]
	v_mov_b32_e32 v182, v100
	v_mov_b32_e32 v183, v108
	v_pk_mul_f32 v[170:171], v[168:169], v[168:169]
	v_pk_add_f32 v[96:97], v[182:183], v[96:97]
	v_mov_b32_e32 v108, v101
	v_lshl_add_u64 v[122:123], v[126:127], 0, s[92:93]
	v_lshlrev_b32_e32 v150, 16, v110
	v_and_b32_e32 v151, 0xffff0000, v110
	v_lshlrev_b32_e32 v166, 16, v102
	v_and_b32_e32 v167, 0xffff0000, v102
	v_pk_add_f32 v[96:97], v[108:109], v[96:97]
	v_mov_b32_e32 v100, v170
	v_mov_b32_e32 v101, v154
	ds_write_b128 v240, v[132:135]
	ds_write_b128 v240, v[136:139] offset:16
	ds_write_b128 v240, v[140:143] offset:32
	ds_write_b128 v240, v[144:147] offset:48
	v_lshl_add_u64 v[244:245], v[122:123], 0, v[242:243]
	ds_read_b128 v[132:135], v241
	ds_read_b128 v[136:139], v241 offset:128
	ds_read_b128 v[140:143], v241 offset:256
	ds_read_b128 v[144:147], v241 offset:384
	s_waitcnt lgkmcnt(0)
; DI unsigned cvt_pk_bf16(float lo, float hi) { const f32x2 v = {lo, hi}; const bf16x2_t b = __builtin_convertvector(v, bf16x2_t); return __builtin_bit_cast(unsigned, b); }
; DI float bflo(unsigned u) { return __uint_as_float(u << 16); }
; DI float bfhi(unsigned u) { return __uint_as_float(u & 0xffff0000u); }
; DI void qkv_post_chunk(const Params& p, unsigned char* lds, int c2) {
;     ...
;             for (int sec = 0; sec < 3; ++sec) {
;                 bf16_t* pp = rowp + sec * 1024 + lane * 16;
;                 const u32x4 v0 = ld[j][sec][0], v1 = ld[j][sec][1];
;                 float x[16];
; #pragma unroll
;                 for (int e = 0; e < 4; ++e) { x[2 * e] = bflo(v0[e]); x[2 * e + 1] = bfhi(v0[e]); x[8 + 2 * e] = bflo(v1[e]); x[8 + 2 * e + 1] = bfhi(v1[e]); }
;                 if (sec < 2) {
;                     float ss = 0.f;
; #pragma unroll
;                     for (int e = 0; e < 16; ++e) ss += x[e] * x[e];
;                     ss += __shfl_xor(ss, 1); ss += __shfl_xor(ss, 2); ss += __shfl_xor(ss, 4);
;                     const float rs = rsqrtf(ss * (1.f / 128.f) + EPS);
; #pragma unroll
;                     for (int e = 0; e < 16; ++e) x[e] = x[e] * rs * (sec == 0 ? qn[e] : kn[e]);
;                     u32x4 w0, w1;
;                     w0.x = cvt_pk_bf16(x[0], x[1]); w0.y = cvt_pk_bf16(x[2], x[3]); w0.z = cvt_pk_bf16(x[4], x[5]); w0.w = cvt_pk_bf16(x[6], x[7]);
;                     w1.x = cvt_pk_bf16(x[8], x[9]); w1.y = cvt_pk_bf16(x[10], x[11]); w1.z = cvt_pk_bf16(x[12], x[13]); w1.w = cvt_pk_bf16(x[14], x[15]);
;                     *(u32x4*)pp = w0; *(u32x4*)(pp + 8) = w1;
;                 }
;                 if (sec >= 1) {
;                     float* o = (sec == 1 ? ko : vo) + ((size_t)(b * 8 + hd) * SL + s0 + tk) * 128 + d0;
; #pragma unroll
;                     for (int e4 = 0; e4 < 4; ++e4) *(f32x4*)(o + 4 * e4) = (f32x4){x[4 * e4], x[4 * e4 + 1], x[4 * e4 + 2], x[4 * e4 + 3]};
;                 }
;                 if (sec == 2) {
; #pragma unroll
;                     for (int e = 0; e < 1; ++e) { *(u32x4*)(VL + tk * 1032 + lane * 16) = v0; *(u32x4*)(VL + tk * 1032 + lane * 16 + 8) = v1; }
	global_store_dwordx4 v[244:245], v[132:135], off
	global_store_dwordx4 v[244:245], v[136:139], off offset:128
	global_store_dwordx4 v[244:245], v[140:143], off offset:256
	global_store_dwordx4 v[244:245], v[144:147], off offset:384
	v_lshlrev_b32_e32 v122, 16, v111
	v_and_b32_e32 v123, 0xffff0000, v111
	v_pk_mul_f32 v[110:111], v[150:151], v[150:151]
	v_lshlrev_b32_e32 v104, 16, v103
	v_and_b32_e32 v105, 0xffff0000, v103
	v_pk_mul_f32 v[102:103], v[166:167], v[166:167]
	v_pk_add_f32 v[96:97], v[100:101], v[96:97]
	v_mov_b32_e32 v154, v171
	v_pk_add_f32 v[96:97], v[154:155], v[96:97]
	v_mov_b32_e32 v100, v102
	v_mov_b32_e32 v101, v110
	v_pk_mul_f32 v[148:149], v[122:123], v[122:123]
	v_pk_mul_f32 v[164:165], v[104:105], v[104:105]
	v_pk_add_f32 v[96:97], v[100:101], v[96:97]
	v_mov_b32_e32 v110, v103
	v_pk_add_f32 v[96:97], v[110:111], v[96:97]
	v_mov_b32_e32 v100, v164
	v_mov_b32_e32 v101, v148
	v_pk_add_f32 v[96:97], v[100:101], v[96:97]
	v_mov_b32_e32 v148, v165
	v_pk_add_f32 v[96:97], v[148:149], v[96:97]
	ds_bpermute_b32 v101, v125, v97
	ds_bpermute_b32 v100, v125, v96
	v_and_b32_e32 v135, 0xffff0000, v95
	v_lshlrev_b32_e32 v134, 16, v95
	v_and_b32_e32 v133, 0xffff0000, v94
	v_lshlrev_b32_e32 v132, 16, v94
	s_waitcnt lgkmcnt(0)
	v_pk_add_f32 v[96:97], v[96:97], v[100:101]
	ds_bpermute_b32 v101, v129, v97
	ds_bpermute_b32 v100, v129, v96
	v_and_b32_e32 v147, 0xffff0000, v89
	v_lshlrev_b32_e32 v146, 16, v89
	v_and_b32_e32 v145, 0xffff0000, v88
	v_lshlrev_b32_e32 v144, 16, v88
	v_lshl_add_u64 v[102:103], v[126:127], 0, s[20:21]
	v_and_b32_e32 v139, 0xffff0000, v91
	v_lshlrev_b32_e32 v138, 16, v91
	v_and_b32_e32 v137, 0xffff0000, v90
	v_lshlrev_b32_e32 v136, 16, v90
	v_and_b32_e32 v143, 0xffff0000, v93
	v_lshlrev_b32_e32 v142, 16, v93
	v_and_b32_e32 v141, 0xffff0000, v92
	v_lshlrev_b32_e32 v140, 16, v92
	ds_write_b128 v240, v[144:147]
	ds_write_b128 v240, v[136:139] offset:16
	ds_write_b128 v240, v[140:143] offset:32
	ds_write_b128 v240, v[132:135] offset:48
	v_lshl_add_u64 v[244:245], v[102:103], 0, v[242:243]
	ds_read_b128 v[144:147], v241
	ds_read_b128 v[136:139], v241 offset:128
	ds_read_b128 v[140:143], v241 offset:256
	ds_read_b128 v[132:135], v241 offset:384
	s_waitcnt lgkmcnt(0)
	global_store_dwordx4 v[244:245], v[144:147], off
	global_store_dwordx4 v[244:245], v[136:139], off offset:128
	global_store_dwordx4 v[244:245], v[140:143], off offset:256
	global_store_dwordx4 v[244:245], v[132:135], off offset:384
	ds_write_b128 v113, v[88:91]
	ds_write_b128 v113, v[92:95] offset:16
	s_waitcnt lgkmcnt(2)
	v_pk_add_f32 v[90:91], v[96:97], v[100:101]
	ds_bpermute_b32 v93, v130, v91
	ds_bpermute_b32 v92, v130, v90
	v_add_u32_e32 v88, 8, v112
	v_add_u32_e32 v89, s25, v88
	v_mad_i64_i32 v[110:111], s[26:27], v89, s91, v[114:115]
	s_waitcnt lgkmcnt(0)
	v_pk_add_f32 v[90:91], v[90:91], v[92:93]
	v_and_b32_e32 v139, 0xffff0000, v80
	v_pk_fma_f32 v[100:101], v[90:91], s[28:29], v[120:121] op_sel_hi:[1,0,0]
	v_and_b32_e32 v155, 0xffff0000, v72
	v_mul_f32_e32 v90, 0x4b800000, v101
	v_cmp_gt_f32_e32 vcc, s22, v101
	v_lshlrev_b32_e32 v138, 16, v80
	v_lshlrev_b32_e32 v154, 16, v72
	v_cndmask_b32_e32 v90, v101, v90, vcc
	v_rsq_f32_e32 v90, v90
	v_lshlrev_b32_e32 v136, 16, v82
	v_and_b32_e32 v137, 0xffff0000, v82
	v_lshlrev_b32_e32 v82, 16, v81
	v_mul_f32_e32 v91, 0x45800000, v90
	v_cndmask_b32_e32 v90, v90, v91, vcc
	v_pk_mul_f32 v[92:93], v[90:91], v[162:163] op_sel_hi:[0,1]
	v_pk_mul_f32 v[96:97], v[90:91], v[160:161] op_sel_hi:[0,1]
	v_pk_mul_f32 v[92:93], v[44:45], v[92:93]
	v_pk_mul_f32 v[94:95], v[90:91], v[106:107] op_sel_hi:[0,1]
	v_pk_mul_f32 v[96:97], v[40:41], v[96:97]
	v_pk_mul_f32 v[102:103], v[90:91], v[158:159] op_sel_hi:[0,1]
	v_pk_mul_f32 v[106:107], v[90:91], v[156:157] op_sel_hi:[0,1]
	v_pk_mul_f32 v[108:109], v[90:91], v[152:153] op_sel_hi:[0,1]
	v_pk_mul_f32 v[126:127], v[90:91], v[150:151] op_sel_hi:[0,1]
	v_pk_mul_f32 v[90:91], v[90:91], v[122:123] op_sel_hi:[0,1]
	v_pk_mul_f32 v[122:123], v[26:27], v[90:91]
	v_cvt_pk_bf16_f32 v90, v92, v93
	v_cvt_pk_bf16_f32 v92, v96, v97
	v_mul_f32_e32 v97, 0x4b800000, v100
	v_cmp_gt_f32_e32 vcc, s22, v100
	v_pk_mul_f32 v[94:95], v[46:47], v[94:95]
	v_pk_mul_f32 v[102:103], v[42:43], v[102:103]
	v_cndmask_b32_e32 v97, v100, v97, vcc
	v_rsq_f32_e32 v100, v97
	v_pk_mul_f32 v[106:107], v[36:37], v[106:107]
	v_pk_mul_f32 v[108:109], v[38:39], v[108:109]
	v_pk_mul_f32 v[126:127], v[24:25], v[126:127]
	v_cvt_pk_bf16_f32 v91, v94, v95
	v_cvt_pk_bf16_f32 v93, v102, v103
	v_cvt_pk_bf16_f32 v94, v106, v107
	v_cvt_pk_bf16_f32 v95, v108, v109
	v_cvt_pk_bf16_f32 v96, v126, v127
	v_cvt_pk_bf16_f32 v97, v122, v123
	ds_write_b128 v246, v[90:93]
	ds_write_b128 v246, v[94:97] offset:16
	v_lshl_add_u64 v[250:251], v[110:111], 0, v[248:249]
	ds_read_b128 v[90:93], v247
	ds_read_b128 v[94:97], v247 offset:1024
	s_waitcnt lgkmcnt(0)
; DI unsigned cvt_pk_bf16(float lo, float hi) { const f32x2 v = {lo, hi}; const bf16x2_t b = __builtin_convertvector(v, bf16x2_t); return __builtin_bit_cast(unsigned, b); }
; DI float bflo(unsigned u) { return __uint_as_float(u << 16); }
; DI float bfhi(unsigned u) { return __uint_as_float(u & 0xffff0000u); }
; DI void qkv_post_chunk(const Params& p, unsigned char* lds, int c2) {
;     ...
;             for (int sec = 0; sec < 3; ++sec) {
;                 bf16_t* pp = rowp + sec * 1024 + lane * 16;
;                 const u32x4 v0 = ld[j][sec][0], v1 = ld[j][sec][1];
;                 float x[16];
; #pragma unroll
;                 for (int e = 0; e < 4; ++e) { x[2 * e] = bflo(v0[e]); x[2 * e + 1] = bfhi(v0[e]); x[8 + 2 * e] = bflo(v1[e]); x[8 + 2 * e + 1] = bfhi(v1[e]); }
;                 if (sec < 2) {
;                     float ss = 0.f;
; #pragma unroll
;                     for (int e = 0; e < 16; ++e) ss += x[e] * x[e];
;                     ss += __shfl_xor(ss, 1); ss += __shfl_xor(ss, 2); ss += __shfl_xor(ss, 4);
;                     const float rs = rsqrtf(ss * (1.f / 128.f) + EPS);
; #pragma unroll
;                     for (int e = 0; e < 16; ++e) x[e] = x[e] * rs * (sec == 0 ? qn[e] : kn[e]);
;                     u32x4 w0, w1;
;                     w0.x = cvt_pk_bf16(x[0], x[1]); w0.y = cvt_pk_bf16(x[2], x[3]); w0.z = cvt_pk_bf16(x[4], x[5]); w0.w = cvt_pk_bf16(x[6], x[7]);
;                     w1.x = cvt_pk_bf16(x[8], x[9]); w1.y = cvt_pk_bf16(x[10], x[11]); w1.z = cvt_pk_bf16(x[12], x[13]); w1.w = cvt_pk_bf16(x[14], x[15]);
;                     *(u32x4*)pp = w0; *(u32x4*)(pp + 8) = w1;
;                 }
;                 if (sec >= 1) {
;                     float* o = (sec == 1 ? ko : vo) + ((size_t)(b * 8 + hd) * SL + s0 + tk) * 128 + d0;
; #pragma unroll
;                     for (int e4 = 0; e4 < 4; ++e4) *(f32x4*)(o + 4 * e4) = (f32x4){x[4 * e4], x[4 * e4 + 1], x[4 * e4 + 2], x[4 * e4 + 3]};
;                 }
	global_store_dwordx4 v[250:251], v[90:93], off
	global_store_dwordx4 v[250:251], v[94:97], off offset:1024
	v_lshlrev_b32_e32 v152, 16, v74
	v_mul_f32_e32 v90, 0x45800000, v100
	v_cndmask_b32_e32 v106, v100, v90, vcc
	v_pk_mul_f32 v[90:91], v[106:107], v[178:179] op_sel_hi:[0,1]
	v_pk_mul_f32 v[92:93], v[106:107], v[98:99] op_sel_hi:[0,1]
	v_pk_mul_f32 v[94:95], v[106:107], v[176:177] op_sel_hi:[0,1]
	v_pk_mul_f32 v[96:97], v[106:107], v[174:175] op_sel_hi:[0,1]
	v_pk_mul_f32 v[102:103], v[106:107], v[166:167] op_sel_hi:[0,1]
	v_pk_mul_f32 v[104:105], v[106:107], v[104:105] op_sel_hi:[0,1]
	v_pk_mul_f32 v[90:91], v[20:21], v[90:91]
	v_pk_mul_f32 v[92:93], v[22:23], v[92:93]
	v_pk_mul_f32 v[94:95], v[16:17], v[94:95]
	v_pk_mul_f32 v[96:97], v[18:19], v[96:97]
	v_pk_mul_f32 v[98:99], v[106:107], v[172:173] op_sel_hi:[0,1]
	v_pk_mul_f32 v[100:101], v[106:107], v[168:169] op_sel_hi:[0,1]
	v_pk_mul_f32 v[102:103], v[0:1], v[102:103]
	v_pk_mul_f32 v[104:105], v[2:3], v[104:105]
	v_mov_b32_e32 v168, v155
	v_mov_b32_e32 v169, v139
	v_pk_mul_f32 v[98:99], v[4:5], v[98:99]
	v_pk_mul_f32 v[100:101], v[6:7], v[100:101]
	v_cvt_pk_bf16_f32 v106, v90, v91
	v_cvt_pk_bf16_f32 v107, v92, v93
	v_cvt_pk_bf16_f32 v108, v94, v95
	v_cvt_pk_bf16_f32 v109, v96, v97
	v_cvt_pk_bf16_f32 v134, v102, v103
	v_cvt_pk_bf16_f32 v135, v104, v105
	v_and_b32_e32 v153, 0xffff0000, v74
	v_lshlrev_b32_e32 v74, 16, v73
	v_mov_b32_e32 v166, v154
	v_mov_b32_e32 v167, v138
	v_pk_mul_f32 v[168:169], v[168:169], v[168:169]
	v_cvt_pk_bf16_f32 v132, v98, v99
	v_cvt_pk_bf16_f32 v133, v100, v101
	ds_write_b128 v246, v[106:109]
	ds_write_b128 v246, v[132:135] offset:16
	v_lshl_add_u64 v[250:251], v[110:111], 0, v[248:249]
	ds_read_b128 v[106:109], v247
	ds_read_b128 v[132:135], v247 offset:1024
	s_waitcnt lgkmcnt(0)
	global_store_dwordx4 v[250:251], v[106:109], off offset:2048
	global_store_dwordx4 v[250:251], v[132:135], off offset:3072
	v_lshlrev_b32_e32 v150, 16, v75
	v_and_b32_e32 v151, 0xffff0000, v75
	v_lshlrev_b32_e32 v134, 16, v83
	v_and_b32_e32 v135, 0xffff0000, v83
	v_and_b32_e32 v83, 0xffff0000, v81
	v_and_b32_e32 v75, 0xffff0000, v73
	v_mov_b32_e32 v162, v74
	v_mov_b32_e32 v163, v82
	v_pk_fma_f32 v[166:167], v[166:167], v[166:167], v[168:169]
	v_mov_b32_e32 v164, v75
	v_mov_b32_e32 v165, v83
	v_pk_fma_f32 v[162:163], v[162:163], v[162:163], v[166:167]
	v_mov_b32_e32 v158, v152
	v_mov_b32_e32 v159, v136
	v_pk_fma_f32 v[162:163], v[164:165], v[164:165], v[162:163]
	v_mov_b32_e32 v160, v153
	v_mov_b32_e32 v161, v137
	v_pk_fma_f32 v[158:159], v[158:159], v[158:159], v[162:163]
	v_ashrrev_i32_e32 v89, 31, v88
	v_lshlrev_b32_e32 v132, 16, v84
	v_and_b32_e32 v133, 0xffff0000, v84
	v_lshlrev_b32_e32 v148, 16, v76
	v_and_b32_e32 v149, 0xffff0000, v76
	v_mov_b32_e32 v72, v150
	v_mov_b32_e32 v73, v134
	v_pk_fma_f32 v[158:159], v[160:161], v[160:161], v[158:159]
	v_lshl_add_u64 v[88:89], v[118:119], 0, v[88:89]
	v_lshlrev_b32_e32 v122, 16, v85
	v_and_b32_e32 v123, 0xffff0000, v85
	v_pk_mul_f32 v[84:85], v[132:133], v[132:133]
	v_lshlrev_b32_e32 v144, 16, v77
	v_and_b32_e32 v145, 0xffff0000, v77
	v_pk_mul_f32 v[76:77], v[148:149], v[148:149]
	v_mov_b32_e32 v156, v151
	v_mov_b32_e32 v157, v135
	v_pk_fma_f32 v[72:73], v[72:73], v[72:73], v[158:159]
	v_lshlrev_b64 v[88:89], 9, v[88:89]
	v_pk_fma_f32 v[72:73], v[156:157], v[156:157], v[72:73]
	v_mov_b32_e32 v156, v76
	v_mov_b32_e32 v157, v84
	v_lshl_add_u64 v[88:89], v[116:117], 0, v[88:89]
	v_pk_mul_f32 v[126:127], v[122:123], v[122:123]
	v_pk_mul_f32 v[146:147], v[144:145], v[144:145]
	v_pk_add_f32 v[72:73], v[156:157], v[72:73]
	v_mov_b32_e32 v84, v77
	v_lshl_add_u64 v[106:107], v[88:89], 0, s[92:93]
	v_lshlrev_b32_e32 v110, 16, v86
	v_and_b32_e32 v111, 0xffff0000, v86
	v_lshlrev_b32_e32 v142, 16, v78
	v_and_b32_e32 v143, 0xffff0000, v78
	v_pk_add_f32 v[72:73], v[84:85], v[72:73]
	v_mov_b32_e32 v76, v146
	v_mov_b32_e32 v77, v126
	ds_write_b128 v240, v[90:93]
	ds_write_b128 v240, v[94:97] offset:16
	ds_write_b128 v240, v[98:101] offset:32
	ds_write_b128 v240, v[102:105] offset:48
	v_lshl_add_u64 v[244:245], v[106:107], 0, v[242:243]
	ds_read_b128 v[90:93], v241
	ds_read_b128 v[94:97], v241 offset:128
	ds_read_b128 v[98:101], v241 offset:256
	ds_read_b128 v[102:105], v241 offset:384
	s_waitcnt lgkmcnt(0)
	global_store_dwordx4 v[244:245], v[90:93], off
	global_store_dwordx4 v[244:245], v[94:97], off offset:128
	global_store_dwordx4 v[244:245], v[98:101], off offset:256
	global_store_dwordx4 v[244:245], v[102:105], off offset:384
	v_lshlrev_b32_e32 v106, 16, v87
	v_and_b32_e32 v107, 0xffff0000, v87
	v_pk_mul_f32 v[86:87], v[110:111], v[110:111]
	v_lshlrev_b32_e32 v80, 16, v79
	v_and_b32_e32 v81, 0xffff0000, v79
	v_pk_mul_f32 v[78:79], v[142:143], v[142:143]
	v_pk_add_f32 v[72:73], v[76:77], v[72:73]
	v_mov_b32_e32 v126, v147
	v_pk_add_f32 v[72:73], v[126:127], v[72:73]
	v_mov_b32_e32 v76, v78
	v_mov_b32_e32 v77, v86
	v_pk_mul_f32 v[108:109], v[106:107], v[106:107]
	v_pk_mul_f32 v[140:141], v[80:81], v[80:81]
	v_pk_add_f32 v[72:73], v[76:77], v[72:73]
	v_mov_b32_e32 v86, v79
	v_pk_add_f32 v[72:73], v[86:87], v[72:73]
	v_mov_b32_e32 v76, v140
	v_mov_b32_e32 v77, v108
	v_pk_add_f32 v[72:73], v[76:77], v[72:73]
	v_mov_b32_e32 v108, v141
	v_pk_add_f32 v[72:73], v[108:109], v[72:73]
	ds_bpermute_b32 v77, v125, v73
	ds_bpermute_b32 v76, v125, v72
	v_and_b32_e32 v93, 0xffff0000, v71
	v_lshlrev_b32_e32 v92, 16, v71
	v_and_b32_e32 v91, 0xffff0000, v70
	v_lshlrev_b32_e32 v90, 16, v70
	s_waitcnt lgkmcnt(0)
; DI unsigned cvt_pk_bf16(float lo, float hi) { const f32x2 v = {lo, hi}; const bf16x2_t b = __builtin_convertvector(v, bf16x2_t); return __builtin_bit_cast(unsigned, b); }
; DI float bflo(unsigned u) { return __uint_as_float(u << 16); }
; DI float bfhi(unsigned u) { return __uint_as_float(u & 0xffff0000u); }
; DI void qkv_post_chunk(const Params& p, unsigned char* lds, int c2) {
;     ...
;             for (int sec = 0; sec < 3; ++sec) {
;                 bf16_t* pp = rowp + sec * 1024 + lane * 16;
;                 const u32x4 v0 = ld[j][sec][0], v1 = ld[j][sec][1];
;                 float x[16];
; #pragma unroll
;                 for (int e = 0; e < 4; ++e) { x[2 * e] = bflo(v0[e]); x[2 * e + 1] = bfhi(v0[e]); x[8 + 2 * e] = bflo(v1[e]); x[8 + 2 * e + 1] = bfhi(v1[e]); }
;                 if (sec < 2) {
;                     float ss = 0.f;
; #pragma unroll
;                     for (int e = 0; e < 16; ++e) ss += x[e] * x[e];
;                     ss += __shfl_xor(ss, 1); ss += __shfl_xor(ss, 2); ss += __shfl_xor(ss, 4);
;                     const float rs = rsqrtf(ss * (1.f / 128.f) + EPS);
; #pragma unroll
;                     for (int e = 0; e < 16; ++e) x[e] = x[e] * rs * (sec == 0 ? qn[e] : kn[e]);
;                     u32x4 w0, w1;
;                     w0.x = cvt_pk_bf16(x[0], x[1]); w0.y = cvt_pk_bf16(x[2], x[3]); w0.z = cvt_pk_bf16(x[4], x[5]); w0.w = cvt_pk_bf16(x[6], x[7]);
;                     w1.x = cvt_pk_bf16(x[8], x[9]); w1.y = cvt_pk_bf16(x[10], x[11]); w1.z = cvt_pk_bf16(x[12], x[13]); w1.w = cvt_pk_bf16(x[14], x[15]);
;                     *(u32x4*)pp = w0; *(u32x4*)(pp + 8) = w1;
;                 }
;                 if (sec >= 1) {
;                     float* o = (sec == 1 ? ko : vo) + ((size_t)(b * 8 + hd) * SL + s0 + tk) * 128 + d0;
; #pragma unroll
;                     for (int e4 = 0; e4 < 4; ++e4) *(f32x4*)(o + 4 * e4) = (f32x4){x[4 * e4], x[4 * e4 + 1], x[4 * e4 + 2], x[4 * e4 + 3]};
;                 }
;                 if (sec == 2) {
; #pragma unroll
;                     for (int e = 0; e < 1; ++e) { *(u32x4*)(VL + tk * 1032 + lane * 16) = v0; *(u32x4*)(VL + tk * 1032 + lane * 16 + 8) = v1; }
	v_pk_add_f32 v[72:73], v[72:73], v[76:77]
	ds_bpermute_b32 v77, v129, v73
	ds_bpermute_b32 v76, v129, v72
	v_and_b32_e32 v105, 0xffff0000, v65
	v_lshlrev_b32_e32 v104, 16, v65
	v_and_b32_e32 v103, 0xffff0000, v64
	v_lshlrev_b32_e32 v102, 16, v64
	v_lshl_add_u64 v[78:79], v[88:89], 0, s[20:21]
	v_and_b32_e32 v97, 0xffff0000, v67
	v_lshlrev_b32_e32 v96, 16, v67
	v_and_b32_e32 v95, 0xffff0000, v66
	v_lshlrev_b32_e32 v94, 16, v66
	v_and_b32_e32 v101, 0xffff0000, v69
	v_lshlrev_b32_e32 v100, 16, v69
	v_and_b32_e32 v99, 0xffff0000, v68
	v_lshlrev_b32_e32 v98, 16, v68
	ds_write_b128 v240, v[102:105]
	ds_write_b128 v240, v[94:97] offset:16
	ds_write_b128 v240, v[98:101] offset:32
	ds_write_b128 v240, v[90:93] offset:48
	v_lshl_add_u64 v[244:245], v[78:79], 0, v[242:243]
	ds_read_b128 v[102:105], v241
	ds_read_b128 v[94:97], v241 offset:128
	ds_read_b128 v[98:101], v241 offset:256
	ds_read_b128 v[90:93], v241 offset:384
	s_waitcnt lgkmcnt(0)
	global_store_dwordx4 v[244:245], v[102:105], off
	global_store_dwordx4 v[244:245], v[94:97], off offset:128
	global_store_dwordx4 v[244:245], v[98:101], off offset:256
	global_store_dwordx4 v[244:245], v[90:93], off offset:384
	ds_write_b128 v113, v[64:67] offset:16512
	ds_write_b128 v113, v[68:71] offset:16528
	s_waitcnt lgkmcnt(2)
	v_pk_add_f32 v[66:67], v[72:73], v[76:77]
	ds_bpermute_b32 v69, v130, v67
	ds_bpermute_b32 v68, v130, v66
	v_add_u32_e32 v64, 16, v112
	v_add_u32_e32 v65, s25, v64
	v_mad_i64_i32 v[90:91], s[26:27], v65, s91, v[114:115]
	s_waitcnt lgkmcnt(0)
	v_pk_add_f32 v[66:67], v[66:67], v[68:69]
	v_and_b32_e32 v99, 0xffff0000, v56
	v_pk_fma_f32 v[76:77], v[66:67], s[28:29], v[120:121] op_sel_hi:[1,0,0]
	v_and_b32_e32 v127, 0xffff0000, v48
	v_mul_f32_e32 v66, 0x4b800000, v77
	v_cmp_gt_f32_e32 vcc, s22, v77
	v_lshlrev_b32_e32 v98, 16, v56
	v_lshlrev_b32_e32 v126, 16, v48
	v_cndmask_b32_e32 v66, v77, v66, vcc
	v_rsq_f32_e32 v66, v66
	v_lshlrev_b32_e32 v96, 16, v58
	v_and_b32_e32 v97, 0xffff0000, v58
	v_lshlrev_b32_e32 v58, 16, v57
	v_mul_f32_e32 v67, 0x45800000, v66
	v_cndmask_b32_e32 v66, v66, v67, vcc
	v_pk_mul_f32 v[68:69], v[66:67], v[138:139] op_sel_hi:[0,1]
	v_pk_mul_f32 v[72:73], v[66:67], v[136:137] op_sel_hi:[0,1]
	v_pk_mul_f32 v[68:69], v[44:45], v[68:69]
	v_pk_mul_f32 v[70:71], v[66:67], v[82:83] op_sel_hi:[0,1]
	v_pk_mul_f32 v[72:73], v[40:41], v[72:73]
	v_pk_mul_f32 v[78:79], v[66:67], v[134:135] op_sel_hi:[0,1]
	v_pk_mul_f32 v[82:83], v[66:67], v[132:133] op_sel_hi:[0,1]
	v_pk_mul_f32 v[84:85], v[66:67], v[122:123] op_sel_hi:[0,1]
	v_pk_mul_f32 v[86:87], v[66:67], v[110:111] op_sel_hi:[0,1]
	v_pk_mul_f32 v[66:67], v[66:67], v[106:107] op_sel_hi:[0,1]
	v_pk_mul_f32 v[88:89], v[26:27], v[66:67]
	v_cvt_pk_bf16_f32 v66, v68, v69
	v_cvt_pk_bf16_f32 v68, v72, v73
	v_mul_f32_e32 v73, 0x4b800000, v76
	v_cmp_gt_f32_e32 vcc, s22, v76
	v_pk_mul_f32 v[70:71], v[46:47], v[70:71]
	v_pk_mul_f32 v[78:79], v[42:43], v[78:79]
	v_cndmask_b32_e32 v73, v76, v73, vcc
	v_rsq_f32_e32 v76, v73
	v_pk_mul_f32 v[82:83], v[36:37], v[82:83]
	v_pk_mul_f32 v[84:85], v[38:39], v[84:85]
	v_pk_mul_f32 v[86:87], v[24:25], v[86:87]
	v_cvt_pk_bf16_f32 v67, v70, v71
	v_cvt_pk_bf16_f32 v69, v78, v79
	v_cvt_pk_bf16_f32 v70, v82, v83
	v_cvt_pk_bf16_f32 v71, v84, v85
	v_cvt_pk_bf16_f32 v72, v86, v87
	v_cvt_pk_bf16_f32 v73, v88, v89
	ds_write_b128 v246, v[66:69]
	ds_write_b128 v246, v[70:73] offset:16
	v_lshl_add_u64 v[250:251], v[90:91], 0, v[248:249]
	ds_read_b128 v[66:69], v247
	ds_read_b128 v[70:73], v247 offset:1024
	s_waitcnt lgkmcnt(0)
	global_store_dwordx4 v[250:251], v[66:69], off
	global_store_dwordx4 v[250:251], v[70:73], off offset:1024
	v_lshlrev_b32_e32 v122, 16, v50
	v_mul_f32_e32 v66, 0x45800000, v76
	v_cndmask_b32_e32 v82, v76, v66, vcc
	v_pk_mul_f32 v[76:77], v[82:83], v[144:145] op_sel_hi:[0,1]
	v_mov_b32_e32 v144, v127
	v_mov_b32_e32 v145, v99
	v_pk_mul_f32 v[78:79], v[82:83], v[142:143] op_sel_hi:[0,1]
	v_and_b32_e32 v123, 0xffff0000, v50
	v_lshlrev_b32_e32 v50, 16, v49
	v_mov_b32_e32 v142, v126
	v_mov_b32_e32 v143, v98
	v_pk_mul_f32 v[144:145], v[144:145], v[144:145]
	v_lshlrev_b32_e32 v94, 16, v59
	v_and_b32_e32 v95, 0xffff0000, v59
	v_and_b32_e32 v59, 0xffff0000, v57
	v_lshlrev_b32_e32 v110, 16, v51
	v_and_b32_e32 v111, 0xffff0000, v51
	v_and_b32_e32 v51, 0xffff0000, v49
	v_mov_b32_e32 v138, v50
	v_mov_b32_e32 v139, v58
	v_pk_fma_f32 v[142:143], v[142:143], v[142:143], v[144:145]
	v_mov_b32_e32 v140, v51
	v_mov_b32_e32 v141, v59
	v_pk_fma_f32 v[138:139], v[138:139], v[138:139], v[142:143]
	v_pk_mul_f32 v[66:67], v[82:83], v[154:155] op_sel_hi:[0,1]
	v_pk_mul_f32 v[68:69], v[82:83], v[74:75] op_sel_hi:[0,1]
	v_pk_mul_f32 v[70:71], v[82:83], v[152:153] op_sel_hi:[0,1]
	v_pk_mul_f32 v[72:73], v[82:83], v[150:151] op_sel_hi:[0,1]
	v_pk_mul_f32 v[80:81], v[82:83], v[80:81] op_sel_hi:[0,1]
	v_mov_b32_e32 v134, v122
	v_mov_b32_e32 v135, v96
	v_pk_fma_f32 v[138:139], v[140:141], v[140:141], v[138:139]
	v_pk_mul_f32 v[66:67], v[20:21], v[66:67]
	v_pk_mul_f32 v[68:69], v[22:23], v[68:69]
	v_pk_mul_f32 v[70:71], v[16:17], v[70:71]
	v_pk_mul_f32 v[72:73], v[18:19], v[72:73]
	v_pk_mul_f32 v[74:75], v[82:83], v[148:149] op_sel_hi:[0,1]
	v_pk_mul_f32 v[78:79], v[0:1], v[78:79]
	v_pk_mul_f32 v[80:81], v[2:3], v[80:81]
	v_mov_b32_e32 v136, v123
	v_mov_b32_e32 v137, v97
	v_pk_fma_f32 v[134:135], v[134:135], v[134:135], v[138:139]
	v_ashrrev_i32_e32 v65, 31, v64
	v_pk_mul_f32 v[74:75], v[4:5], v[74:75]
	v_pk_mul_f32 v[76:77], v[6:7], v[76:77]
	v_cvt_pk_bf16_f32 v82, v66, v67
	v_cvt_pk_bf16_f32 v83, v68, v69
	v_cvt_pk_bf16_f32 v84, v70, v71
	v_cvt_pk_bf16_f32 v85, v72, v73
	v_cvt_pk_bf16_f32 v88, v78, v79
	v_cvt_pk_bf16_f32 v89, v80, v81
	v_lshlrev_b32_e32 v92, 16, v60
	v_and_b32_e32 v93, 0xffff0000, v60
	v_lshlrev_b32_e32 v108, 16, v52
	v_and_b32_e32 v109, 0xffff0000, v52
	v_mov_b32_e32 v48, v110
	v_mov_b32_e32 v49, v94
	v_pk_fma_f32 v[134:135], v[136:137], v[136:137], v[134:135]
	v_lshl_add_u64 v[64:65], v[118:119], 0, v[64:65]
	v_cvt_pk_bf16_f32 v86, v74, v75
	v_cvt_pk_bf16_f32 v87, v76, v77
	ds_write_b128 v246, v[82:85]
	ds_write_b128 v246, v[86:89] offset:16
	v_lshl_add_u64 v[250:251], v[90:91], 0, v[248:249]
	ds_read_b128 v[82:85], v247
	ds_read_b128 v[86:89], v247 offset:1024
	s_waitcnt lgkmcnt(0)
; DI unsigned cvt_pk_bf16(float lo, float hi) { const f32x2 v = {lo, hi}; const bf16x2_t b = __builtin_convertvector(v, bf16x2_t); return __builtin_bit_cast(unsigned, b); }
; DI float bflo(unsigned u) { return __uint_as_float(u << 16); }
; DI float bfhi(unsigned u) { return __uint_as_float(u & 0xffff0000u); }
; DI void qkv_post_chunk(const Params& p, unsigned char* lds, int c2) {
;     ...
;             for (int sec = 0; sec < 3; ++sec) {
;                 bf16_t* pp = rowp + sec * 1024 + lane * 16;
;                 const u32x4 v0 = ld[j][sec][0], v1 = ld[j][sec][1];
;                 float x[16];
; #pragma unroll
;                 for (int e = 0; e < 4; ++e) { x[2 * e] = bflo(v0[e]); x[2 * e + 1] = bfhi(v0[e]); x[8 + 2 * e] = bflo(v1[e]); x[8 + 2 * e + 1] = bfhi(v1[e]); }
;                 if (sec < 2) {
;                     float ss = 0.f;
; #pragma unroll
;                     for (int e = 0; e < 16; ++e) ss += x[e] * x[e];
;                     ss += __shfl_xor(ss, 1); ss += __shfl_xor(ss, 2); ss += __shfl_xor(ss, 4);
;                     const float rs = rsqrtf(ss * (1.f / 128.f) + EPS);
; #pragma unroll
;                     for (int e = 0; e < 16; ++e) x[e] = x[e] * rs * (sec == 0 ? qn[e] : kn[e]);
;                     u32x4 w0, w1;
;                     w0.x = cvt_pk_bf16(x[0], x[1]); w0.y = cvt_pk_bf16(x[2], x[3]); w0.z = cvt_pk_bf16(x[4], x[5]); w0.w = cvt_pk_bf16(x[6], x[7]);
;                     w1.x = cvt_pk_bf16(x[8], x[9]); w1.y = cvt_pk_bf16(x[10], x[11]); w1.z = cvt_pk_bf16(x[12], x[13]); w1.w = cvt_pk_bf16(x[14], x[15]);
;                     *(u32x4*)pp = w0; *(u32x4*)(pp + 8) = w1;
;                 }
;                 if (sec >= 1) {
;                     float* o = (sec == 1 ? ko : vo) + ((size_t)(b * 8 + hd) * SL + s0 + tk) * 128 + d0;
; #pragma unroll
;                     for (int e4 = 0; e4 < 4; ++e4) *(f32x4*)(o + 4 * e4) = (f32x4){x[4 * e4], x[4 * e4 + 1], x[4 * e4 + 2], x[4 * e4 + 3]};
;                 }
;                 if (sec == 2) {
; #pragma unroll
;                     for (int e = 0; e < 1; ++e) { *(u32x4*)(VL + tk * 1032 + lane * 16) = v0; *(u32x4*)(VL + tk * 1032 + lane * 16 + 8) = v1; }
	global_store_dwordx4 v[250:251], v[82:85], off offset:2048
	global_store_dwordx4 v[250:251], v[86:89], off offset:3072
	v_lshlrev_b32_e32 v104, 16, v53
	v_and_b32_e32 v105, 0xffff0000, v53
	v_lshlrev_b32_e32 v88, 16, v61
	v_and_b32_e32 v89, 0xffff0000, v61
	v_pk_mul_f32 v[60:61], v[92:93], v[92:93]
	v_pk_mul_f32 v[52:53], v[108:109], v[108:109]
	v_mov_b32_e32 v132, v111
	v_mov_b32_e32 v133, v95
	v_pk_fma_f32 v[48:49], v[48:49], v[48:49], v[134:135]
	v_lshlrev_b64 v[64:65], 9, v[64:65]
	v_pk_fma_f32 v[48:49], v[132:133], v[132:133], v[48:49]
	v_mov_b32_e32 v132, v52
	v_mov_b32_e32 v133, v60
	v_lshl_add_u64 v[64:65], v[116:117], 0, v[64:65]
	v_pk_mul_f32 v[90:91], v[88:89], v[88:89]
	v_pk_mul_f32 v[106:107], v[104:105], v[104:105]
	v_pk_add_f32 v[48:49], v[132:133], v[48:49]
	v_mov_b32_e32 v60, v53
	v_lshl_add_u64 v[82:83], v[64:65], 0, s[92:93]
	v_lshlrev_b32_e32 v86, 16, v62
	v_and_b32_e32 v87, 0xffff0000, v62
	v_lshlrev_b32_e32 v102, 16, v54
	v_and_b32_e32 v103, 0xffff0000, v54
	v_pk_add_f32 v[48:49], v[60:61], v[48:49]
	v_mov_b32_e32 v52, v106
	v_mov_b32_e32 v53, v90
	ds_write_b128 v240, v[66:69]
	ds_write_b128 v240, v[70:73] offset:16
	ds_write_b128 v240, v[74:77] offset:32
	ds_write_b128 v240, v[78:81] offset:48
	v_lshl_add_u64 v[244:245], v[82:83], 0, v[242:243]
	ds_read_b128 v[66:69], v241
	ds_read_b128 v[70:73], v241 offset:128
	ds_read_b128 v[74:77], v241 offset:256
	ds_read_b128 v[78:81], v241 offset:384
	s_waitcnt lgkmcnt(0)
	global_store_dwordx4 v[244:245], v[66:69], off
	global_store_dwordx4 v[244:245], v[70:73], off offset:128
	global_store_dwordx4 v[244:245], v[74:77], off offset:256
	global_store_dwordx4 v[244:245], v[78:81], off offset:384
	v_lshlrev_b32_e32 v82, 16, v63
	v_and_b32_e32 v83, 0xffff0000, v63
	v_pk_mul_f32 v[62:63], v[86:87], v[86:87]
	v_lshlrev_b32_e32 v56, 16, v55
	v_and_b32_e32 v57, 0xffff0000, v55
	v_pk_mul_f32 v[54:55], v[102:103], v[102:103]
	v_pk_add_f32 v[48:49], v[52:53], v[48:49]
	v_mov_b32_e32 v90, v107
	v_pk_add_f32 v[48:49], v[90:91], v[48:49]
	v_mov_b32_e32 v52, v54
	v_mov_b32_e32 v53, v62
	v_pk_mul_f32 v[84:85], v[82:83], v[82:83]
	v_pk_mul_f32 v[100:101], v[56:57], v[56:57]
	v_pk_add_f32 v[48:49], v[52:53], v[48:49]
	v_mov_b32_e32 v62, v55
	v_pk_add_f32 v[48:49], v[62:63], v[48:49]
	v_mov_b32_e32 v52, v100
	v_mov_b32_e32 v53, v84
	v_pk_add_f32 v[48:49], v[52:53], v[48:49]
	v_mov_b32_e32 v84, v101
	v_pk_add_f32 v[48:49], v[84:85], v[48:49]
	ds_bpermute_b32 v53, v125, v49
	ds_bpermute_b32 v52, v125, v48
	v_and_b32_e32 v69, 0xffff0000, v15
	v_lshlrev_b32_e32 v68, 16, v15
	v_and_b32_e32 v67, 0xffff0000, v14
	v_lshlrev_b32_e32 v66, 16, v14
	s_waitcnt lgkmcnt(0)
	v_pk_add_f32 v[48:49], v[48:49], v[52:53]
	ds_bpermute_b32 v53, v129, v49
	ds_bpermute_b32 v52, v129, v48
	v_and_b32_e32 v81, 0xffff0000, v9
	v_lshlrev_b32_e32 v80, 16, v9
	v_and_b32_e32 v79, 0xffff0000, v8
	v_lshlrev_b32_e32 v78, 16, v8
	v_lshl_add_u64 v[54:55], v[64:65], 0, s[20:21]
	v_and_b32_e32 v73, 0xffff0000, v11
	v_lshlrev_b32_e32 v72, 16, v11
	v_and_b32_e32 v71, 0xffff0000, v10
	v_lshlrev_b32_e32 v70, 16, v10
	v_and_b32_e32 v77, 0xffff0000, v13
	v_lshlrev_b32_e32 v76, 16, v13
	v_and_b32_e32 v75, 0xffff0000, v12
	v_lshlrev_b32_e32 v74, 16, v12
	ds_write_b128 v240, v[78:81]
	ds_write_b128 v240, v[70:73] offset:16
	ds_write_b128 v240, v[74:77] offset:32
	ds_write_b128 v240, v[66:69] offset:48
	v_lshl_add_u64 v[244:245], v[54:55], 0, v[242:243]
	ds_read_b128 v[78:81], v241
	ds_read_b128 v[70:73], v241 offset:128
	ds_read_b128 v[74:77], v241 offset:256
	ds_read_b128 v[66:69], v241 offset:384
	s_waitcnt lgkmcnt(0)
	global_store_dwordx4 v[244:245], v[78:81], off
	global_store_dwordx4 v[244:245], v[70:73], off offset:128
	global_store_dwordx4 v[244:245], v[74:77], off offset:256
	global_store_dwordx4 v[244:245], v[66:69], off offset:384
	ds_write_b128 v113, v[8:11] offset:33024
	ds_write_b128 v113, v[12:15] offset:33040
	s_waitcnt lgkmcnt(2)
	v_pk_add_f32 v[10:11], v[48:49], v[52:53]
	ds_bpermute_b32 v13, v130, v11
	ds_bpermute_b32 v12, v130, v10
	v_add_u32_e32 v8, 24, v112
	v_add_u32_e32 v9, s25, v8
	v_mad_i64_i32 v[48:49], s[24:25], v9, s91, v[114:115]
	s_waitcnt lgkmcnt(0)
; DI unsigned cvt_pk_bf16(float lo, float hi) { const f32x2 v = {lo, hi}; const bf16x2_t b = __builtin_convertvector(v, bf16x2_t); return __builtin_bit_cast(unsigned, b); }
; DI float bflo(unsigned u) { return __uint_as_float(u << 16); }
; DI float bfhi(unsigned u) { return __uint_as_float(u & 0xffff0000u); }
; DI void qkv_post_chunk(const Params& p, unsigned char* lds, int c2) {
;     ...
;             for (int sec = 0; sec < 3; ++sec) {
;                 bf16_t* pp = rowp + sec * 1024 + lane * 16;
;                 const u32x4 v0 = ld[j][sec][0], v1 = ld[j][sec][1];
;                 float x[16];
; #pragma unroll
;                 for (int e = 0; e < 4; ++e) { x[2 * e] = bflo(v0[e]); x[2 * e + 1] = bfhi(v0[e]); x[8 + 2 * e] = bflo(v1[e]); x[8 + 2 * e + 1] = bfhi(v1[e]); }
;                 if (sec < 2) {
;                     float ss = 0.f;
; #pragma unroll
;                     for (int e = 0; e < 16; ++e) ss += x[e] * x[e];
;                     ss += __shfl_xor(ss, 1); ss += __shfl_xor(ss, 2); ss += __shfl_xor(ss, 4);
;                     const float rs = rsqrtf(ss * (1.f / 128.f) + EPS);
; #pragma unroll
;                     for (int e = 0; e < 16; ++e) x[e] = x[e] * rs * (sec == 0 ? qn[e] : kn[e]);
;                     u32x4 w0, w1;
;                     w0.x = cvt_pk_bf16(x[0], x[1]); w0.y = cvt_pk_bf16(x[2], x[3]); w0.z = cvt_pk_bf16(x[4], x[5]); w0.w = cvt_pk_bf16(x[6], x[7]);
;                     w1.x = cvt_pk_bf16(x[8], x[9]); w1.y = cvt_pk_bf16(x[10], x[11]); w1.z = cvt_pk_bf16(x[12], x[13]); w1.w = cvt_pk_bf16(x[14], x[15]);
;                     *(u32x4*)pp = w0; *(u32x4*)(pp + 8) = w1;
;                 }
;                 if (sec >= 1) {
;                     float* o = (sec == 1 ? ko : vo) + ((size_t)(b * 8 + hd) * SL + s0 + tk) * 128 + d0;
; #pragma unroll
;                     for (int e4 = 0; e4 < 4; ++e4) *(f32x4*)(o + 4 * e4) = (f32x4){x[4 * e4], x[4 * e4 + 1], x[4 * e4 + 2], x[4 * e4 + 3]};
;                 }
;                 if (sec == 2) {
; #pragma unroll
;                     for (int e = 0; e < 1; ++e) { *(u32x4*)(VL + tk * 1032 + lane * 16) = v0; *(u32x4*)(VL + tk * 1032 + lane * 16 + 8) = v1; }
;                 }
;             }
;         }
;     }
;     __syncthreads();
	v_pk_add_f32 v[10:11], v[10:11], v[12:13]
	v_ashrrev_i32_e32 v9, 31, v8
	v_pk_fma_f32 v[52:53], v[10:11], s[28:29], v[120:121] op_sel_hi:[1,0,0]
	v_lshl_add_u64 v[8:9], v[118:119], 0, v[8:9]
	v_mul_f32_e32 v10, 0x4b800000, v53
	v_cmp_gt_f32_e32 vcc, s22, v53
	v_lshlrev_b64 v[8:9], 9, v[8:9]
	v_lshl_add_u64 v[54:55], v[116:117], 0, v[8:9]
	v_cndmask_b32_e32 v10, v53, v10, vcc
	v_rsq_f32_e32 v10, v10
	s_nop 0
	v_mul_f32_e32 v8, 0x45800000, v10
	v_cndmask_b32_e32 v8, v10, v8, vcc
	v_pk_mul_f32 v[14:15], v[8:9], v[96:97] op_sel_hi:[0,1]
	v_pk_mul_f32 v[14:15], v[40:41], v[14:15]
	v_pk_mul_f32 v[40:41], v[8:9], v[94:95] op_sel_hi:[0,1]
	v_pk_mul_f32 v[40:41], v[42:43], v[40:41]
	v_pk_mul_f32 v[42:43], v[8:9], v[92:93] op_sel_hi:[0,1]
	v_pk_mul_f32 v[10:11], v[8:9], v[98:99] op_sel_hi:[0,1]
	v_pk_mul_f32 v[36:37], v[36:37], v[42:43]
	v_pk_mul_f32 v[42:43], v[8:9], v[88:89] op_sel_hi:[0,1]
	v_pk_mul_f32 v[10:11], v[44:45], v[10:11]
	v_pk_mul_f32 v[12:13], v[8:9], v[58:59] op_sel_hi:[0,1]
	v_pk_mul_f32 v[38:39], v[38:39], v[42:43]
	v_pk_mul_f32 v[42:43], v[8:9], v[86:87] op_sel_hi:[0,1]
	v_pk_mul_f32 v[8:9], v[8:9], v[82:83] op_sel_hi:[0,1]
	v_pk_mul_f32 v[26:27], v[26:27], v[8:9]
	v_cvt_pk_bf16_f32 v8, v10, v11
	v_cvt_pk_bf16_f32 v10, v14, v15
	v_mul_f32_e32 v15, 0x4b800000, v52
	v_cmp_gt_f32_e32 vcc, s22, v52
	v_pk_mul_f32 v[24:25], v[24:25], v[42:43]
	v_pk_mul_f32 v[12:13], v[46:47], v[12:13]
	v_cndmask_b32_e32 v15, v52, v15, vcc
	v_cvt_pk_bf16_f32 v14, v24, v25
	v_rsq_f32_e32 v24, v15
	v_cvt_pk_bf16_f32 v9, v12, v13
	v_cvt_pk_bf16_f32 v11, v40, v41
	v_cvt_pk_bf16_f32 v12, v36, v37
	v_cvt_pk_bf16_f32 v13, v38, v39
	v_cvt_pk_bf16_f32 v15, v26, v27
	ds_write_b128 v246, v[8:11]
	ds_write_b128 v246, v[12:15] offset:16
	v_lshl_add_u64 v[250:251], v[48:49], 0, v[248:249]
	ds_read_b128 v[8:11], v247
	ds_read_b128 v[12:15], v247 offset:1024
	s_waitcnt lgkmcnt(0)
	global_store_dwordx4 v[250:251], v[8:11], off
	global_store_dwordx4 v[250:251], v[12:15], off offset:1024
	s_nop 0
	v_mul_f32_e32 v8, 0x45800000, v24
	v_cndmask_b32_e32 v24, v24, v8, vcc
	v_pk_mul_f32 v[12:13], v[24:25], v[122:123] op_sel_hi:[0,1]
	v_pk_mul_f32 v[12:13], v[16:17], v[12:13]
	v_pk_mul_f32 v[16:17], v[24:25], v[108:109] op_sel_hi:[0,1]
	v_pk_mul_f32 v[4:5], v[4:5], v[16:17]
	v_pk_mul_f32 v[16:17], v[24:25], v[104:105] op_sel_hi:[0,1]
	v_pk_mul_f32 v[8:9], v[24:25], v[126:127] op_sel_hi:[0,1]
	v_pk_mul_f32 v[10:11], v[24:25], v[50:51] op_sel_hi:[0,1]
	v_pk_mul_f32 v[14:15], v[24:25], v[110:111] op_sel_hi:[0,1]
	v_pk_mul_f32 v[6:7], v[6:7], v[16:17]
	v_pk_mul_f32 v[16:17], v[24:25], v[102:103] op_sel_hi:[0,1]
	v_pk_mul_f32 v[8:9], v[20:21], v[8:9]
	v_pk_mul_f32 v[10:11], v[22:23], v[10:11]
	v_pk_mul_f32 v[14:15], v[18:19], v[14:15]
	v_pk_mul_f32 v[0:1], v[0:1], v[16:17]
	v_pk_mul_f32 v[16:17], v[24:25], v[56:57] op_sel_hi:[0,1]
	v_pk_mul_f32 v[2:3], v[2:3], v[16:17]
	v_cvt_pk_bf16_f32 v16, v8, v9
	v_cvt_pk_bf16_f32 v17, v10, v11
	v_cvt_pk_bf16_f32 v18, v12, v13
	v_cvt_pk_bf16_f32 v19, v14, v15
	v_cvt_pk_bf16_f32 v20, v4, v5
	v_cvt_pk_bf16_f32 v21, v6, v7
	v_cvt_pk_bf16_f32 v22, v0, v1
	v_cvt_pk_bf16_f32 v23, v2, v3
	ds_write_b128 v246, v[16:19]
	ds_write_b128 v246, v[20:23] offset:16
	v_lshl_add_u64 v[250:251], v[48:49], 0, v[248:249]
	ds_read_b128 v[16:19], v247
	ds_read_b128 v[20:23], v247 offset:1024
	s_waitcnt lgkmcnt(0)
	global_store_dwordx4 v[250:251], v[16:19], off offset:2048
	global_store_dwordx4 v[250:251], v[20:23], off offset:3072
	v_cmp_gt_i32_e32 vcc, s15, v128
	v_lshl_add_u64 v[16:17], v[54:55], 0, s[92:93]
	ds_write_b128 v240, v[8:11]
	ds_write_b128 v240, v[12:15] offset:16
	ds_write_b128 v240, v[4:7] offset:32
	ds_write_b128 v240, v[0:3] offset:48
	v_lshl_add_u64 v[244:245], v[16:17], 0, v[242:243]
	ds_read_b128 v[8:11], v241
	ds_read_b128 v[12:15], v241 offset:128
	ds_read_b128 v[4:7], v241 offset:256
	ds_read_b128 v[0:3], v241 offset:384
	s_waitcnt lgkmcnt(0)
	global_store_dwordx4 v[244:245], v[8:11], off
	global_store_dwordx4 v[244:245], v[12:15], off offset:128
	global_store_dwordx4 v[244:245], v[4:7], off offset:256
	global_store_dwordx4 v[244:245], v[0:3], off offset:384
	s_waitcnt vmcnt(45)
	v_and_b32_e32 v15, 0xffff0000, v33
	v_lshlrev_b32_e32 v14, 16, v33
	v_and_b32_e32 v13, 0xffff0000, v32
	v_lshlrev_b32_e32 v12, 16, v32
	v_lshl_add_u64 v[16:17], v[54:55], 0, s[20:21]
	s_waitcnt vmcnt(44)
	v_and_b32_e32 v3, 0xffff0000, v31
	v_lshlrev_b32_e32 v2, 16, v31
	v_and_b32_e32 v7, 0xffff0000, v35
	v_lshlrev_b32_e32 v6, 16, v35
	v_and_b32_e32 v1, 0xffff0000, v30
	v_lshlrev_b32_e32 v0, 16, v30
	v_and_b32_e32 v5, 0xffff0000, v34
	v_lshlrev_b32_e32 v4, 16, v34
	v_and_b32_e32 v11, 0xffff0000, v29
	v_lshlrev_b32_e32 v10, 16, v29
	v_and_b32_e32 v9, 0xffff0000, v28
	v_lshlrev_b32_e32 v8, 16, v28
	ds_write_b128 v240, v[12:15]
	ds_write_b128 v240, v[4:7] offset:16
	ds_write_b128 v240, v[8:11] offset:32
	ds_write_b128 v240, v[0:3] offset:48
	v_lshl_add_u64 v[244:245], v[16:17], 0, v[242:243]
	ds_read_b128 v[12:15], v241
	ds_read_b128 v[4:7], v241 offset:128
	ds_read_b128 v[8:11], v241 offset:256
	ds_read_b128 v[0:3], v241 offset:384
	s_waitcnt lgkmcnt(0)
	global_store_dwordx4 v[244:245], v[12:15], off
	global_store_dwordx4 v[244:245], v[4:7], off offset:128
	global_store_dwordx4 v[244:245], v[8:11], off offset:256
	global_store_dwordx4 v[244:245], v[0:3], off offset:384
	ds_write_b128 v113, v[32:35] offset:49536
	ds_write_b128 v113, v[28:31] offset:49552
	s_waitcnt lgkmcnt(0)
	s_barrier
	s_and_saveexec_b64 s[20:21], vcc
	s_cbranch_execz .LBB0_115
	s_add_u32 s18, s88, s18
	s_addc_u32 s19, s89, s19
	s_bitset1_b32 s16, 10
	s_and_b64 s[4:5], exec, s[4:5]
	s_cselect_b32 s16, s16, s17
	v_and_b32_e32 v0, 31, v128
	s_mov_b64 s[4:5], 0
